# P6/P12: residual-stream row stores without the nt hint
# speedup vs baseline: 1.0047x; 1.0047x over previous
.LBB0_756:
	v_ashrrev_i32_e32 v73, 31, v72
	v_lshlrev_b64 v[86:87], 12, v[72:73]
	v_lshl_add_u64 v[32:33], v[74:75], 0, v[86:87]
	global_load_dwordx2 v[56:57], v[32:33], off
	global_load_dwordx2 v[58:59], v[32:33], off offset:512
	global_load_dwordx2 v[60:61], v[32:33], off offset:1024
	global_load_dwordx2 v[62:63], v[32:33], off offset:1536
	global_load_dwordx2 v[64:65], v[32:33], off offset:2560
	global_load_dwordx2 v[66:67], v[32:33], off offset:2048
	global_load_dwordx2 v[68:69], v[32:33], off offset:3584
	global_load_dwordx2 v[84:85], v[32:33], off offset:3072
	v_lshlrev_b64 v[88:89], 13, v[72:73]
	v_lshl_add_u64 v[32:33], v[80:81], 0, v[88:89]
	v_add_co_u32_e32 v94, vcc, s3, v32
	global_load_dwordx4 v[52:55], v[32:33], off nt
	global_load_dwordx4 v[48:51], v[32:33], off offset:1024 nt
	global_load_dwordx4 v[44:47], v[32:33], off offset:2048 nt
	global_load_dwordx4 v[40:43], v[32:33], off offset:3072 nt
	v_addc_co_u32_e32 v95, vcc, 0, v33, vcc
	global_load_dwordx4 v[36:39], v[94:95], off nt
	global_load_dwordx4 v[32:35], v[94:95], off offset:1024 nt
	global_load_dwordx4 v[90:93], v[94:95], off offset:2048 nt
	v_lshl_add_u64 v[88:89], v[76:77], 0, v[88:89]
	global_load_dwordx4 v[94:97], v[94:95], off offset:3072 nt
	v_lshl_add_u64 v[86:87], v[78:79], 0, v[86:87]
	s_waitcnt vmcnt(0)
	v_and_b32_e32 v99, 0xffff0000, v56
	v_and_b32_e32 v101, 0xffff0000, v58
	v_lshlrev_b32_e32 v98, 16, v56
	v_lshlrev_b32_e32 v100, 16, v58
	v_and_b32_e32 v103, 0xffff0000, v60
	v_lshlrev_b32_e32 v56, 16, v57
	v_lshlrev_b32_e32 v71, 16, v68
	v_and_b32_e32 v115, 0xffff0000, v68
	v_lshlrev_b32_e32 v117, 16, v69
	v_and_b32_e32 v119, 0xffff0000, v69
	v_mul_f32_e32 v68, v99, v99
	v_mul_f32_e32 v69, v101, v101
	v_lshlrev_b32_e32 v58, 16, v59
	v_lshlrev_b32_e32 v102, 16, v60
	v_and_b32_e32 v105, 0xffff0000, v62
	v_mul_f32_e32 v73, v103, v103
	v_fmac_f32_e32 v68, v98, v98
	v_fmac_f32_e32 v69, v100, v100
	v_and_b32_e32 v57, 0xffff0000, v57
	v_and_b32_e32 v59, 0xffff0000, v59
	v_lshlrev_b32_e32 v60, 16, v61
	v_lshlrev_b32_e32 v104, 16, v62
	v_and_b32_e32 v109, 0xffff0000, v64
	v_and_b32_e32 v108, 0xffff0000, v66
	v_lshlrev_b32_e32 v70, 16, v84
	v_and_b32_e32 v114, 0xffff0000, v84
	v_mul_f32_e32 v84, v105, v105
	v_fmac_f32_e32 v73, v102, v102
	v_fmac_f32_e32 v68, v56, v56
	v_fmac_f32_e32 v69, v58, v58
	v_and_b32_e32 v61, 0xffff0000, v61
	v_lshlrev_b32_e32 v62, 16, v63
	v_lshlrev_b32_e32 v107, 16, v64
	v_lshlrev_b32_e32 v106, 16, v66
	v_lshlrev_b32_e32 v111, 16, v65
	v_and_b32_e32 v113, 0xffff0000, v65
	v_pk_mul_f32 v[64:65], v[108:109], v[108:109]
	v_fmac_f32_e32 v84, v104, v104
	v_fmac_f32_e32 v73, v60, v60
	v_fmac_f32_e32 v68, v57, v57
	v_fmac_f32_e32 v69, v59, v59
	v_and_b32_e32 v63, 0xffff0000, v63
	v_lshlrev_b32_e32 v110, 16, v67
	v_pk_fma_f32 v[64:65], v[106:107], v[106:107], v[64:65]
	v_fmac_f32_e32 v84, v62, v62
	v_fmac_f32_e32 v73, v61, v61
	v_add_f32_e32 v68, v68, v69
	v_and_b32_e32 v112, 0xffff0000, v67
	v_pk_mul_f32 v[66:67], v[114:115], v[114:115]
	v_pk_fma_f32 v[64:65], v[110:111], v[110:111], v[64:65]
	v_fmac_f32_e32 v84, v63, v63
	v_add_f32_e32 v68, v68, v73
	v_lshlrev_b32_e32 v116, 16, v85
	v_pk_fma_f32 v[66:67], v[70:71], v[70:71], v[66:67]
	v_pk_fma_f32 v[64:65], v[112:113], v[112:113], v[64:65]
	v_add_f32_e32 v68, v68, v84
	v_and_b32_e32 v118, 0xffff0000, v85
	v_pk_fma_f32 v[66:67], v[116:117], v[116:117], v[66:67]
	v_add_f32_e32 v64, v68, v64
	v_pk_fma_f32 v[66:67], v[118:119], v[118:119], v[66:67]
	v_add_f32_e32 v64, v64, v65
	v_add_f32_e32 v64, v64, v66
	v_add_f32_e32 v64, v64, v67
	ds_bpermute_b32 v65, v83, v64
	v_mov_b32_e32 v124, v106
	v_mov_b32_e32 v126, v110
	v_mov_b32_e32 v127, v112
	v_mov_b32_e32 v112, v111
	s_waitcnt lgkmcnt(0)
	v_add_f32_e32 v64, v64, v65
	ds_bpermute_b32 v65, v132, v64
	s_waitcnt lgkmcnt(0)
	v_add_f32_e32 v64, v64, v65
	ds_bpermute_b32 v65, v133, v64
	s_waitcnt lgkmcnt(0)
	v_add_f32_e32 v66, v64, v65
	v_add_u32_e32 v64, 1, v72
	ds_bpermute_b32 v67, v134, v66
	v_ashrrev_i32_e32 v65, 31, v64
	v_lshlrev_b64 v[84:85], 12, v[64:65]
	v_lshl_add_u64 v[68:69], v[74:75], 0, v[84:85]
	global_load_dwordx2 v[120:121], v[68:69], off
	global_load_dwordx2 v[122:123], v[68:69], off offset:512
	global_load_dwordx2 v[138:139], v[68:69], off offset:1024
	global_load_dwordx2 v[140:141], v[68:69], off offset:1536
	s_waitcnt lgkmcnt(0)
	v_add_f32_e32 v66, v66, v67
	ds_bpermute_b32 v67, v135, v66
	v_add_u32_e32 v72, s13, v72
	s_waitcnt lgkmcnt(0)
	v_add_f32_e32 v73, v66, v67
	global_load_dwordx2 v[142:143], v[68:69], off offset:2048
	global_load_dwordx2 v[144:145], v[68:69], off offset:2560
	global_load_dwordx2 v[66:67], v[68:69], off offset:3072
	s_nop 0
	global_load_dwordx2 v[68:69], v[68:69], off offset:3584
	ds_bpermute_b32 v125, v136, v73
	s_waitcnt lgkmcnt(0)
	v_add_f32_e32 v73, v73, v125
	v_fmamk_f32 v73, v73, 0x3a000000, v82
	v_mul_f32_e32 v106, 0x4b800000, v73
	v_cmp_gt_f32_e32 vcc, s14, v73
	v_mov_b32_e32 v125, v108
	v_mov_b32_e32 v108, v107
	v_cndmask_b32_e32 v73, v73, v106, vcc
	v_rsq_f32_e32 v73, v73
	s_waitcnt vmcnt(7)
	v_and_b32_e32 v164, 0xffff0000, v120
	v_mul_f32_e32 v106, 0x45800000, v73
	v_cndmask_b32_e32 v106, v73, v106, vcc
	v_pk_mul_f32 v[98:99], v[98:99], v[106:107] op_sel_hi:[1,0]
	v_pk_mul_f32 v[102:103], v[102:103], v[106:107] op_sel_hi:[1,0]
	v_pk_mul_f32 v[124:125], v[124:125], v[106:107] op_sel_hi:[1,0]
	v_pk_mul_f32 v[56:57], v[56:57], v[106:107] op_sel_hi:[1,0]
	v_pk_mul_f32 v[128:129], v[60:61], v[106:107] op_sel_hi:[1,0]
	v_pk_mul_f32 v[126:127], v[126:127], v[106:107] op_sel_hi:[1,0]
	v_pk_fma_f32 v[60:61], v[0:1], v[98:99], v[52:53]
	v_pk_fma_f32 v[52:53], v[8:9], v[102:103], v[44:45]
	v_pk_fma_f32 v[44:45], v[16:17], v[124:125], v[36:37]
	v_pk_mul_f32 v[36:37], v[108:109], v[106:107] op_sel_hi:[1,0]
	v_pk_mul_f32 v[130:131], v[62:63], v[106:107] op_sel_hi:[1,0]
	v_pk_fma_f32 v[62:63], v[2:3], v[56:57], v[54:55]
	v_pk_fma_f32 v[54:55], v[10:11], v[128:129], v[46:47]
	v_pk_fma_f32 v[46:47], v[18:19], v[126:127], v[38:39]
	v_pk_mul_f32 v[38:39], v[112:113], v[106:107] op_sel_hi:[1,0]
	v_pk_fma_f32 v[32:33], v[20:21], v[36:37], v[32:33]
	v_pk_mul_f32 v[100:101], v[100:101], v[106:107] op_sel_hi:[1,0]
	v_pk_fma_f32 v[34:35], v[22:23], v[38:39], v[34:35]
	v_mov_b32_e32 v38, v33
	v_mov_b32_e32 v39, v45
	v_pk_mul_f32 v[58:59], v[58:59], v[106:107] op_sel_hi:[1,0]
	v_pk_fma_f32 v[56:57], v[4:5], v[100:101], v[48:49]
	v_mov_b32_e32 v36, v32
	v_mov_b32_e32 v37, v44
	v_pk_mul_f32 v[38:39], v[38:39], v[38:39]
	v_pk_fma_f32 v[58:59], v[6:7], v[58:59], v[50:51]
	v_pk_fma_f32 v[50:51], v[14:15], v[130:131], v[42:43]
	v_pk_fma_f32 v[36:37], v[36:37], v[36:37], v[38:39]
	v_mov_b32_e32 v38, v34
	v_mov_b32_e32 v39, v46
	s_waitcnt vmcnt(6)
	v_and_b32_e32 v130, 0xffff0000, v122
	v_mov_b32_e32 v165, v61
	v_mov_b32_e32 v131, v57
	v_pk_fma_f32 v[36:37], v[38:39], v[38:39], v[36:37]
	v_mov_b32_e32 v38, v35
	v_mov_b32_e32 v39, v47
	v_lshlrev_b32_e32 v162, 16, v120
	v_lshlrev_b32_e32 v126, 16, v122
	v_mov_b32_e32 v163, v60
	v_pk_mul_f32 v[100:101], v[164:165], v[164:165]
	v_mov_b32_e32 v127, v56
	v_pk_mul_f32 v[102:103], v[130:131], v[130:131]
	v_pk_mul_f32 v[104:105], v[104:105], v[106:107] op_sel_hi:[1,0]
	v_pk_fma_f32 v[146:147], v[38:39], v[38:39], v[36:37]
	v_mov_b32_e32 v36, v70
	v_mov_b32_e32 v37, v114
	v_mov_b32_e32 v114, v71
	v_lshlrev_b32_e32 v166, 16, v121
	v_lshlrev_b32_e32 v124, 16, v123
	v_pk_fma_f32 v[100:101], v[162:163], v[162:163], v[100:101]
	v_mov_b32_e32 v167, v62
	v_pk_fma_f32 v[102:103], v[126:127], v[126:127], v[102:103]
	v_mov_b32_e32 v125, v58
	v_pk_fma_f32 v[48:49], v[12:13], v[104:105], v[40:41]
	v_pk_mul_f32 v[36:37], v[36:37], v[106:107] op_sel_hi:[1,0]
	v_pk_mul_f32 v[40:41], v[114:115], v[106:107] op_sel_hi:[1,0]
	v_and_b32_e32 v168, 0xffff0000, v121
	v_and_b32_e32 v128, 0xffff0000, v123
	v_pk_fma_f32 v[100:101], v[166:167], v[166:167], v[100:101]
	v_mov_b32_e32 v169, v63
	v_pk_fma_f32 v[102:103], v[124:125], v[124:125], v[102:103]
	v_mov_b32_e32 v129, v59
	v_mov_b32_e32 v38, v116
	v_mov_b32_e32 v39, v118
	v_pk_fma_f32 v[36:37], v[24:25], v[36:37], v[90:91]
	v_mov_b32_e32 v118, v117
	v_pk_fma_f32 v[40:41], v[28:29], v[40:41], v[94:95]
	s_waitcnt vmcnt(5)
	v_and_b32_e32 v122, 0xffff0000, v138
	v_pk_fma_f32 v[100:101], v[168:169], v[168:169], v[100:101]
	v_pk_fma_f32 v[102:103], v[128:129], v[128:129], v[102:103]
	v_mov_b32_e32 v123, v53
	v_pk_mul_f32 v[38:39], v[38:39], v[106:107] op_sel_hi:[1,0]
	v_pk_mul_f32 v[42:43], v[118:119], v[106:107] op_sel_hi:[1,0]
	v_mov_b32_e32 v90, v41
	v_mov_b32_e32 v91, v37
	v_lshlrev_b32_e32 v118, 16, v138
	v_pk_add_f32 v[100:101], v[100:101], v[102:103]
	v_mov_b32_e32 v119, v52
	v_pk_mul_f32 v[102:103], v[122:123], v[122:123]
	v_pk_fma_f32 v[38:39], v[26:27], v[38:39], v[92:93]
	v_pk_fma_f32 v[42:43], v[30:31], v[42:43], v[96:97]
	v_mov_b32_e32 v70, v40
	v_mov_b32_e32 v71, v36
	v_pk_mul_f32 v[90:91], v[90:91], v[90:91]
	v_lshlrev_b32_e32 v116, 16, v139
	v_pk_fma_f32 v[102:103], v[118:119], v[118:119], v[102:103]
	v_mov_b32_e32 v117, v54
	v_pk_fma_f32 v[70:71], v[70:71], v[70:71], v[90:91]
	v_mov_b32_e32 v90, v42
	v_mov_b32_e32 v91, v38
	v_and_b32_e32 v120, 0xffff0000, v139
	v_pk_fma_f32 v[102:103], v[116:117], v[116:117], v[102:103]
	v_mov_b32_e32 v121, v55
	v_pk_fma_f32 v[70:71], v[90:91], v[90:91], v[70:71]
	v_mov_b32_e32 v90, v43
	v_mov_b32_e32 v91, v39
	s_waitcnt vmcnt(4)
	v_and_b32_e32 v114, 0xffff0000, v140
	s_waitcnt vmcnt(2)
	v_and_b32_e32 v95, 0xffff0000, v144
	v_and_b32_e32 v94, 0xffff0000, v142
	v_pk_fma_f32 v[102:103], v[120:121], v[120:121], v[102:103]
	v_mov_b32_e32 v115, v49
	v_pk_fma_f32 v[70:71], v[90:91], v[90:91], v[70:71]
	v_lshlrev_b32_e32 v110, 16, v140
	v_lshlrev_b32_e32 v91, 16, v144
	v_lshlrev_b32_e32 v90, 16, v142
	v_pk_mul_f32 v[92:93], v[94:95], v[94:95]
	v_pk_add_f32 v[100:101], v[102:103], v[100:101]
	v_mov_b32_e32 v111, v48
	v_pk_mul_f32 v[102:103], v[114:115], v[114:115]
	v_lshlrev_b32_e32 v108, 16, v141
	v_lshlrev_b32_e32 v97, 16, v145
	v_lshlrev_b32_e32 v96, 16, v143
	v_pk_fma_f32 v[92:93], v[90:91], v[90:91], v[92:93]
	v_pk_fma_f32 v[102:103], v[110:111], v[110:111], v[102:103]
	v_mov_b32_e32 v109, v50
	v_and_b32_e32 v112, 0xffff0000, v141
	v_and_b32_e32 v99, 0xffff0000, v145
	v_and_b32_e32 v98, 0xffff0000, v143
	v_pk_fma_f32 v[92:93], v[96:97], v[96:97], v[92:93]
	v_pk_fma_f32 v[102:103], v[108:109], v[108:109], v[102:103]
	v_mov_b32_e32 v113, v51
	v_pk_fma_f32 v[92:93], v[98:99], v[98:99], v[92:93]
	v_pk_fma_f32 v[102:103], v[112:113], v[112:113], v[102:103]
	s_waitcnt vmcnt(1)
	v_lshlrev_b32_e32 v104, 16, v67
	v_pk_add_f32 v[100:101], v[102:103], v[100:101]
	v_mov_b32_e32 v102, v92
	v_mov_b32_e32 v103, v147
	v_pk_add_f32 v[138:139], v[100:101], v[102:103]
	s_waitcnt vmcnt(0)
	v_and_b32_e32 v103, 0xffff0000, v68
	v_and_b32_e32 v102, 0xffff0000, v66
	v_lshlrev_b32_e32 v101, 16, v68
	v_lshlrev_b32_e32 v100, 16, v66
	v_and_b32_e32 v106, 0xffff0000, v67
	v_pk_mul_f32 v[66:67], v[102:103], v[102:103]
	v_lshlrev_b32_e32 v105, 16, v69
	v_pk_fma_f32 v[66:67], v[100:101], v[100:101], v[66:67]
	v_and_b32_e32 v107, 0xffff0000, v69
	v_pk_fma_f32 v[66:67], v[104:105], v[104:105], v[66:67]
	v_pk_mov_b32 v[68:69], v[92:93], v[146:147] op_sel:[1,0]
	v_pk_fma_f32 v[66:67], v[106:107], v[106:107], v[66:67]
	v_pk_add_f32 v[68:69], v[138:139], v[68:69]
	v_mov_b32_e32 v92, v66
	v_mov_b32_e32 v93, v71
	v_pk_add_f32 v[68:69], v[68:69], v[92:93]
	v_lshlrev_b64 v[92:93], 13, v[64:65]
	v_lshl_add_u64 v[64:65], v[80:81], 0, v[92:93]
	v_pk_mov_b32 v[66:67], v[66:67], v[70:71] op_sel:[1,0]
	global_load_dwordx4 v[138:141], v[64:65], off nt
	global_load_dwordx4 v[142:145], v[64:65], off offset:1024 nt
	global_load_dwordx4 v[146:149], v[64:65], off offset:2048 nt
	global_load_dwordx4 v[150:153], v[64:65], off offset:3072 nt
	v_pk_add_f32 v[66:67], v[68:69], v[66:67]
	ds_bpermute_b32 v69, v83, v67
	ds_bpermute_b32 v68, v83, v66
	v_add_co_u32_e32 v64, vcc, s3, v64
	v_mov_b32_e32 v163, v164
	s_nop 0
	v_addc_co_u32_e32 v65, vcc, 0, v65, vcc
	s_waitcnt lgkmcnt(0)
	v_pk_add_f32 v[66:67], v[66:67], v[68:69]
	ds_bpermute_b32 v69, v132, v67
	ds_bpermute_b32 v68, v132, v66
	v_mov_b32_e32 v127, v130
	v_mov_b32_e32 v167, v168
	v_mov_b32_e32 v125, v128
	v_mov_b32_e32 v119, v122
	s_waitcnt lgkmcnt(0)
	v_pk_add_f32 v[66:67], v[66:67], v[68:69]
	ds_bpermute_b32 v69, v133, v67
	ds_bpermute_b32 v68, v133, v66
	v_mov_b32_e32 v117, v120
	v_mov_b32_e32 v111, v114
	v_mov_b32_e32 v109, v112
	s_waitcnt lgkmcnt(0)
	v_pk_add_f32 v[170:171], v[66:67], v[68:69]
	global_load_dwordx4 v[154:157], v[64:65], off nt
	global_load_dwordx4 v[158:161], v[64:65], off offset:1024 nt
	global_load_dwordx4 v[68:71], v[64:65], off offset:2048 nt
	s_nop 0
	global_load_dwordx4 v[64:67], v[64:65], off offset:3072 nt
	ds_bpermute_b32 v173, v134, v171
	ds_bpermute_b32 v172, v134, v170
	global_store_dwordx4 v[88:89], v[60:63], off
	global_store_dwordx4 v[88:89], v[56:59], off offset:1024
	global_store_dwordx4 v[88:89], v[52:55], off offset:2048
	global_store_dwordx4 v[88:89], v[48:51], off offset:3072
	v_add_co_u32_e32 v88, vcc, s3, v88
	s_waitcnt lgkmcnt(0)
	v_pk_add_f32 v[170:171], v[170:171], v[172:173]
	ds_bpermute_b32 v173, v135, v171
	ds_bpermute_b32 v172, v135, v170
	v_addc_co_u32_e32 v89, vcc, 0, v89, vcc
	global_store_dwordx4 v[88:89], v[44:47], off
	global_store_dwordx4 v[88:89], v[32:35], off offset:1024
	global_store_dwordx4 v[88:89], v[36:39], off offset:2048
	global_store_dwordx4 v[88:89], v[40:43], off offset:3072
	s_waitcnt lgkmcnt(0)
	v_pk_add_f32 v[170:171], v[170:171], v[172:173]
	ds_bpermute_b32 v173, v136, v171
	ds_bpermute_b32 v172, v136, v170
	s_waitcnt lgkmcnt(0)
	v_pk_add_f32 v[170:171], v[170:171], v[172:173]
	s_nop 0
	v_pk_fma_f32 v[170:171], v[170:171], s[12:13], v[82:83] op_sel_hi:[1,0,0]
	s_nop 0
	v_mul_f32_e32 v73, 0x4b800000, v171
	v_cmp_gt_f32_e32 vcc, s14, v171
	s_nop 1
	v_cndmask_b32_e32 v73, v171, v73, vcc
	v_rsq_f32_e32 v73, v73
	s_nop 0
	v_mul_f32_e32 v88, 0x45800000, v73
	v_cndmask_b32_e32 v88, v73, v88, vcc
	v_pk_mul_f32 v[44:45], v[44:45], v[88:89] op_sel_hi:[1,0]
	v_pk_mul_f32 v[48:49], v[48:49], v[88:89] op_sel_hi:[1,0]
	v_pk_mul_f32 v[50:51], v[50:51], v[88:89] op_sel_hi:[1,0]
	v_cvt_pk_bf16_f32 v44, v44, v45
	v_mul_f32_e32 v45, 0x4b800000, v170
	v_cmp_gt_f32_e32 vcc, s14, v170
	v_cvt_pk_bf16_f32 v48, v48, v49
	v_cvt_pk_bf16_f32 v49, v50, v51
	v_cndmask_b32_e32 v45, v170, v45, vcc
	global_store_dwordx2 v[86:87], v[48:49], off offset:1536
	v_rsq_f32_e32 v48, v45
	v_pk_mul_f32 v[46:47], v[46:47], v[88:89] op_sel_hi:[1,0]
	v_pk_mul_f32 v[52:53], v[52:53], v[88:89] op_sel_hi:[1,0]
	v_cvt_pk_bf16_f32 v45, v46, v47
	global_store_dwordx2 v[86:87], v[44:45], off offset:2048
	v_mul_f32_e32 v44, 0x45800000, v48
	v_cndmask_b32_e32 v170, v48, v44, vcc
	v_pk_mul_f32 v[54:55], v[54:55], v[88:89] op_sel_hi:[1,0]
	v_pk_mul_f32 v[44:45], v[162:163], v[170:171] op_sel_hi:[1,0]
	v_pk_mul_f32 v[48:49], v[126:127], v[170:171] op_sel_hi:[1,0]
	v_cvt_pk_bf16_f32 v52, v52, v53
	v_cvt_pk_bf16_f32 v53, v54, v55
	s_waitcnt vmcnt(17)
	v_pk_fma_f32 v[44:45], v[0:1], v[44:45], v[138:139]
	s_waitcnt vmcnt(16)
	v_pk_fma_f32 v[48:49], v[4:5], v[48:49], v[142:143]
	global_store_dwordx2 v[86:87], v[52:53], off offset:1024
	v_pk_mul_f32 v[46:47], v[166:167], v[170:171] op_sel_hi:[1,0]
	v_mul_f32_e32 v52, v45, v45
	v_pk_mul_f32 v[50:51], v[124:125], v[170:171] op_sel_hi:[1,0]
	v_mul_f32_e32 v53, v49, v49
	v_pk_fma_f32 v[46:47], v[2:3], v[46:47], v[140:141]
	v_fmac_f32_e32 v52, v44, v44
	v_pk_fma_f32 v[50:51], v[6:7], v[50:51], v[144:145]
	v_fmac_f32_e32 v53, v48, v48
	v_pk_mul_f32 v[56:57], v[56:57], v[88:89] op_sel_hi:[1,0]
	v_pk_mul_f32 v[58:59], v[58:59], v[88:89] op_sel_hi:[1,0]
	v_fmac_f32_e32 v52, v46, v46
	v_fmac_f32_e32 v53, v50, v50
	v_cvt_pk_bf16_f32 v56, v56, v57
	v_cvt_pk_bf16_f32 v57, v58, v59
	v_fmac_f32_e32 v52, v47, v47
	v_fmac_f32_e32 v53, v51, v51
	global_store_dwordx2 v[86:87], v[56:57], off offset:512
	v_add_f32_e32 v56, v52, v53
	v_pk_mul_f32 v[52:53], v[118:119], v[170:171] op_sel_hi:[1,0]
	v_pk_mul_f32 v[54:55], v[116:117], v[170:171] op_sel_hi:[1,0]
	s_waitcnt vmcnt(17)
	v_pk_fma_f32 v[52:53], v[8:9], v[52:53], v[146:147]
	v_pk_fma_f32 v[54:55], v[10:11], v[54:55], v[148:149]
	v_mul_f32_e32 v57, v53, v53
	v_fmac_f32_e32 v57, v52, v52
	v_pk_mul_f32 v[60:61], v[60:61], v[88:89] op_sel_hi:[1,0]
	v_pk_mul_f32 v[62:63], v[62:63], v[88:89] op_sel_hi:[1,0]
	v_fmac_f32_e32 v57, v54, v54
	v_cvt_pk_bf16_f32 v60, v60, v61
	v_cvt_pk_bf16_f32 v61, v62, v63
	v_fmac_f32_e32 v57, v55, v55
	global_store_dwordx2 v[86:87], v[60:61], off
	v_add_f32_e32 v60, v57, v56
	v_pk_mul_f32 v[56:57], v[110:111], v[170:171] op_sel_hi:[1,0]
	v_pk_mul_f32 v[58:59], v[108:109], v[170:171] op_sel_hi:[1,0]
	s_waitcnt vmcnt(17)
	v_pk_fma_f32 v[56:57], v[12:13], v[56:57], v[150:151]
	v_pk_fma_f32 v[58:59], v[14:15], v[58:59], v[152:153]
	v_mul_f32_e32 v61, v57, v57
	v_fmac_f32_e32 v61, v56, v56
	v_fmac_f32_e32 v61, v58, v58
	v_fmac_f32_e32 v61, v59, v59
	v_add_f32_e32 v73, v61, v60
	v_mov_b32_e32 v60, v90
	v_mov_b32_e32 v61, v94
	v_mov_b32_e32 v63, v98
	v_mov_b32_e32 v94, v91
	v_mov_b32_e32 v98, v97
	v_pk_mul_f32 v[60:61], v[60:61], v[170:171] op_sel_hi:[1,0]
	v_pk_mul_f32 v[90:91], v[94:95], v[170:171] op_sel_hi:[1,0]
	v_pk_mul_f32 v[94:95], v[98:99], v[170:171] op_sel_hi:[1,0]
	v_mov_b32_e32 v62, v96
	s_waitcnt vmcnt(16)
	v_pk_fma_f32 v[60:61], v[16:17], v[60:61], v[154:155]
	s_waitcnt vmcnt(15)
	v_pk_fma_f32 v[96:97], v[22:23], v[94:95], v[160:161]
	v_pk_fma_f32 v[94:95], v[20:21], v[90:91], v[158:159]
	v_pk_mul_f32 v[62:63], v[62:63], v[170:171] op_sel_hi:[1,0]
	v_mov_b32_e32 v98, v95
	v_mov_b32_e32 v99, v61
	v_pk_fma_f32 v[62:63], v[18:19], v[62:63], v[156:157]
	v_mov_b32_e32 v90, v94
	v_mov_b32_e32 v91, v60
	v_pk_mul_f32 v[98:99], v[98:99], v[98:99]
	s_nop 0
	v_pk_fma_f32 v[90:91], v[90:91], v[90:91], v[98:99]
	v_mov_b32_e32 v98, v96
	v_mov_b32_e32 v99, v62
	v_pk_fma_f32 v[90:91], v[98:99], v[98:99], v[90:91]
	v_mov_b32_e32 v98, v97
	v_mov_b32_e32 v99, v63
	v_pk_fma_f32 v[90:91], v[98:99], v[98:99], v[90:91]
	v_mov_b32_e32 v98, v104
	v_add_f32_e32 v73, v91, v73
	v_add_f32_e32 v73, v90, v73
	v_mov_b32_e32 v90, v100
	v_mov_b32_e32 v91, v102
	v_pk_mul_f32 v[90:91], v[90:91], v[170:171] op_sel_hi:[1,0]
	v_mov_b32_e32 v99, v106
	v_mov_b32_e32 v102, v101
	v_pk_mul_f32 v[98:99], v[98:99], v[170:171] op_sel_hi:[1,0]
	s_waitcnt vmcnt(14)
	v_pk_fma_f32 v[68:69], v[24:25], v[90:91], v[68:69]
	v_pk_mul_f32 v[90:91], v[102:103], v[170:171] op_sel_hi:[1,0]
	v_mov_b32_e32 v106, v105
	v_pk_fma_f32 v[70:71], v[26:27], v[98:99], v[70:71]
	v_pk_mul_f32 v[98:99], v[106:107], v[170:171] op_sel_hi:[1,0]
	s_waitcnt vmcnt(13)
	v_pk_fma_f32 v[64:65], v[28:29], v[90:91], v[64:65]
	v_pk_fma_f32 v[66:67], v[30:31], v[98:99], v[66:67]
	v_mov_b32_e32 v98, v65
	v_mov_b32_e32 v99, v69
	v_mov_b32_e32 v90, v64
	v_mov_b32_e32 v91, v68
	v_pk_mul_f32 v[98:99], v[98:99], v[98:99]
	s_nop 0
	v_pk_fma_f32 v[90:91], v[90:91], v[90:91], v[98:99]
	v_mov_b32_e32 v98, v66
	v_mov_b32_e32 v99, v70
	v_pk_fma_f32 v[90:91], v[98:99], v[98:99], v[90:91]
	v_mov_b32_e32 v98, v67
	v_mov_b32_e32 v99, v71
	v_pk_fma_f32 v[90:91], v[98:99], v[98:99], v[90:91]
	s_nop 0
	v_add_f32_e32 v73, v91, v73
	v_add_f32_e32 v73, v90, v73
	ds_bpermute_b32 v89, v83, v73
	s_waitcnt lgkmcnt(0)
	v_add_f32_e32 v73, v73, v89
	v_pk_mul_f32 v[32:33], v[32:33], v[88:89] op_sel_hi:[1,0]
	v_pk_mul_f32 v[34:35], v[34:35], v[88:89] op_sel_hi:[1,0]
	ds_bpermute_b32 v89, v132, v73
	v_cvt_pk_bf16_f32 v32, v32, v33
	v_cvt_pk_bf16_f32 v33, v34, v35
	global_store_dwordx2 v[86:87], v[32:33], off offset:2560
	s_waitcnt lgkmcnt(0)
	v_pk_mul_f32 v[32:33], v[36:37], v[88:89] op_sel_hi:[1,0]
	v_add_f32_e32 v36, v73, v89
	ds_bpermute_b32 v37, v133, v36
	v_pk_mul_f32 v[34:35], v[38:39], v[88:89] op_sel_hi:[1,0]
	v_cvt_pk_bf16_f32 v32, v32, v33
	v_cvt_pk_bf16_f32 v33, v34, v35
	global_store_dwordx2 v[86:87], v[32:33], off offset:3072
	s_waitcnt lgkmcnt(0)
	v_add_f32_e32 v36, v36, v37
	ds_bpermute_b32 v37, v134, v36
	v_pk_mul_f32 v[32:33], v[40:41], v[88:89] op_sel_hi:[1,0]
	v_pk_mul_f32 v[34:35], v[42:43], v[88:89] op_sel_hi:[1,0]
	v_cvt_pk_bf16_f32 v32, v32, v33
	v_cvt_pk_bf16_f32 v33, v34, v35
	s_waitcnt lgkmcnt(0)
	v_add_f32_e32 v34, v36, v37
	ds_bpermute_b32 v35, v135, v34
	global_store_dwordx2 v[86:87], v[32:33], off offset:3584
	v_lshl_add_u64 v[32:33], v[76:77], 0, v[92:93]
	global_store_dwordx4 v[32:33], v[44:47], off
	global_store_dwordx4 v[32:33], v[48:51], off offset:1024
	global_store_dwordx4 v[32:33], v[52:55], off offset:2048
	global_store_dwordx4 v[32:33], v[56:59], off offset:3072
	v_add_co_u32_e32 v32, vcc, s3, v32
	s_waitcnt lgkmcnt(0)
	v_add_f32_e32 v34, v34, v35
	ds_bpermute_b32 v35, v136, v34
	v_addc_co_u32_e32 v33, vcc, 0, v33, vcc
	global_store_dwordx4 v[32:33], v[60:63], off
	global_store_dwordx4 v[32:33], v[94:97], off offset:1024
	global_store_dwordx4 v[32:33], v[68:71], off offset:2048
	global_store_dwordx4 v[32:33], v[64:67], off offset:3072
	s_waitcnt lgkmcnt(0)
	v_add_f32_e32 v34, v34, v35
	v_fmamk_f32 v34, v34, 0x3a000000, v82
	v_mul_f32_e32 v35, 0x4b800000, v34
	v_cmp_gt_f32_e32 vcc, s14, v34
	s_nop 1
	v_cndmask_b32_e32 v34, v34, v35, vcc
	v_rsq_f32_e32 v34, v34
	s_nop 0
	v_mul_f32_e32 v32, 0x45800000, v34
	v_cndmask_b32_e32 v32, v34, v32, vcc
	v_pk_mul_f32 v[36:37], v[44:45], v[32:33] op_sel_hi:[1,0]
	v_pk_mul_f32 v[38:39], v[46:47], v[32:33] op_sel_hi:[1,0]
	v_lshl_add_u64 v[34:35], v[78:79], 0, v[84:85]
	v_cvt_pk_bf16_f32 v36, v36, v37
	v_cvt_pk_bf16_f32 v37, v38, v39
	global_store_dwordx2 v[34:35], v[36:37], off
	v_pk_mul_f32 v[36:37], v[48:49], v[32:33] op_sel_hi:[1,0]
	v_pk_mul_f32 v[38:39], v[50:51], v[32:33] op_sel_hi:[1,0]
	v_cvt_pk_bf16_f32 v36, v36, v37
	v_cvt_pk_bf16_f32 v37, v38, v39
	global_store_dwordx2 v[34:35], v[36:37], off offset:512
	v_pk_mul_f32 v[36:37], v[52:53], v[32:33] op_sel_hi:[1,0]
	v_pk_mul_f32 v[38:39], v[54:55], v[32:33] op_sel_hi:[1,0]
	v_cvt_pk_bf16_f32 v36, v36, v37
	v_cvt_pk_bf16_f32 v37, v38, v39
	global_store_dwordx2 v[34:35], v[36:37], off offset:1024
	v_pk_mul_f32 v[36:37], v[56:57], v[32:33] op_sel_hi:[1,0]
	v_pk_mul_f32 v[38:39], v[58:59], v[32:33] op_sel_hi:[1,0]
	v_cvt_pk_bf16_f32 v36, v36, v37
	v_cvt_pk_bf16_f32 v37, v38, v39
	global_store_dwordx2 v[34:35], v[36:37], off offset:1536
	v_pk_mul_f32 v[36:37], v[60:61], v[32:33] op_sel_hi:[1,0]
	v_pk_mul_f32 v[38:39], v[62:63], v[32:33] op_sel_hi:[1,0]
	v_cvt_pk_bf16_f32 v36, v36, v37
	v_cvt_pk_bf16_f32 v37, v38, v39
	global_store_dwordx2 v[34:35], v[36:37], off offset:2048
	v_pk_mul_f32 v[36:37], v[94:95], v[32:33] op_sel_hi:[1,0]
	v_pk_mul_f32 v[38:39], v[96:97], v[32:33] op_sel_hi:[1,0]
	v_cvt_pk_bf16_f32 v36, v36, v37
	v_cvt_pk_bf16_f32 v37, v38, v39
	global_store_dwordx2 v[34:35], v[36:37], off offset:2560
	v_pk_mul_f32 v[36:37], v[68:69], v[32:33] op_sel_hi:[1,0]
	v_pk_mul_f32 v[38:39], v[70:71], v[32:33] op_sel_hi:[1,0]
	v_cvt_pk_bf16_f32 v36, v36, v37
	v_cvt_pk_bf16_f32 v37, v38, v39
	global_store_dwordx2 v[34:35], v[36:37], off offset:3072
	v_pk_mul_f32 v[36:37], v[64:65], v[32:33] op_sel_hi:[1,0]
	v_pk_mul_f32 v[32:33], v[66:67], v[32:33] op_sel_hi:[1,0]
	v_cmp_lt_i32_e32 vcc, s15, v72
	v_cvt_pk_bf16_f32 v36, v36, v37
	v_cvt_pk_bf16_f32 v37, v32, v33
	s_or_b64 s[10:11], vcc, s[10:11]
	global_store_dwordx2 v[34:35], v[36:37], off offset:3584
	s_andn2_b64 exec, exec, s[10:11]
	s_cbranch_execnz .LBB0_756

.LBB0_1491:
	v_ashrrev_i32_e32 v49, 31, v48
	v_lshlrev_b64 v[32:33], 12, v[48:49]
	v_lshl_add_u64 v[32:33], v[50:51], 0, v[32:33]
	v_add_u32_e32 v44, 1, v48
	global_load_dwordx2 v[46:47], v[32:33], off offset:2560
	global_load_dwordx2 v[56:57], v[32:33], off offset:2048
	global_load_dwordx2 v[58:59], v[32:33], off offset:3584
	global_load_dwordx2 v[60:61], v[32:33], off offset:3072
	global_load_dwordx2 v[62:63], v[32:33], off
	global_load_dwordx2 v[76:77], v[32:33], off offset:512
	global_load_dwordx2 v[104:105], v[32:33], off offset:1024
	v_ashrrev_i32_e32 v45, 31, v44
	v_lshlrev_b64 v[34:35], 12, v[44:45]
	v_lshl_add_u64 v[64:65], v[50:51], 0, v[34:35]
	global_load_dwordx2 v[106:107], v[64:65], off offset:2560
	global_load_dwordx2 v[108:109], v[64:65], off offset:2048
	global_load_dwordx2 v[110:111], v[64:65], off
	global_load_dwordx2 v[112:113], v[64:65], off offset:512
	global_load_dwordx2 v[114:115], v[64:65], off offset:1024
	global_load_dwordx2 v[122:123], v[64:65], off offset:1536
	global_load_dwordx2 v[120:121], v[32:33], off offset:1536
	v_lshlrev_b64 v[32:33], 13, v[48:49]
	v_lshl_add_u64 v[100:101], v[52:53], 0, v[32:33]
	global_load_dwordx4 v[40:43], v[100:101], off nt
	global_load_dwordx4 v[36:39], v[100:101], off offset:1024 nt
	global_load_dwordx4 v[32:35], v[100:101], off offset:2048 nt
	global_load_dwordx2 v[130:131], v[64:65], off offset:3072
	global_load_dwordx2 v[132:133], v[64:65], off offset:3584
	v_add_co_u32_e32 v178, vcc, s3, v100
	v_lshlrev_b64 v[44:45], 13, v[44:45]
	s_nop 0
	v_addc_co_u32_e32 v179, vcc, 0, v101, vcc
	v_lshl_add_u64 v[180:181], v[52:53], 0, v[44:45]
	v_add_u32_e32 v48, s4, v48
	s_waitcnt vmcnt(0)
	v_and_b32_e32 v83, 0xffff0000, v46
	v_lshlrev_b32_e32 v78, 16, v56
	v_and_b32_e32 v67, 0xffff0000, v58
	v_and_b32_e32 v66, 0xffff0000, v60
	v_and_b32_e32 v82, 0xffff0000, v56
	v_lshlrev_b32_e32 v94, 16, v57
	v_and_b32_e32 v98, 0xffff0000, v57
	v_lshlrev_b32_e32 v65, 16, v58
	v_lshlrev_b32_e32 v64, 16, v60
	v_pk_mul_f32 v[116:117], v[66:67], v[66:67]
	v_and_b32_e32 v57, 0xffff0000, v106
	v_and_b32_e32 v56, 0xffff0000, v108
	v_lshlrev_b32_e32 v69, 16, v59
	v_lshlrev_b32_e32 v68, 16, v61
	v_and_b32_e32 v71, 0xffff0000, v59
	v_and_b32_e32 v70, 0xffff0000, v61
	v_lshlrev_b32_e32 v73, 16, v62
	v_and_b32_e32 v81, 0xffff0000, v62
	v_lshlrev_b32_e32 v87, 16, v63
	v_and_b32_e32 v97, 0xffff0000, v63
	v_lshlrev_b32_e32 v59, 16, v106
	v_lshlrev_b32_e32 v58, 16, v108
	v_lshlrev_b32_e32 v63, 16, v107
	v_lshlrev_b32_e32 v62, 16, v109
	v_and_b32_e32 v61, 0xffff0000, v107
	v_and_b32_e32 v60, 0xffff0000, v109
	v_pk_fma_f32 v[106:107], v[64:65], v[64:65], v[116:117]
	v_pk_mul_f32 v[108:109], v[56:57], v[56:57]
	v_pk_fma_f32 v[106:107], v[68:69], v[68:69], v[106:107]
	v_pk_fma_f32 v[108:109], v[58:59], v[58:59], v[108:109]
	v_and_b32_e32 v85, 0xffff0000, v76
	v_and_b32_e32 v80, 0xffff0000, v110
	v_and_b32_e32 v84, 0xffff0000, v112
	v_pk_fma_f32 v[134:135], v[70:71], v[70:71], v[106:107]
	v_pk_fma_f32 v[106:107], v[62:63], v[62:63], v[108:109]
	v_lshlrev_b32_e32 v75, 16, v76
	v_lshlrev_b32_e32 v72, 16, v110
	v_lshlrev_b32_e32 v74, 16, v112
	v_pk_fma_f32 v[136:137], v[60:61], v[60:61], v[106:107]
	v_pk_mul_f32 v[106:107], v[80:81], v[80:81]
	v_pk_mul_f32 v[108:109], v[84:85], v[84:85]
	v_lshlrev_b32_e32 v91, 16, v77
	v_lshlrev_b32_e32 v86, 16, v111
	v_lshlrev_b32_e32 v90, 16, v113
	v_pk_fma_f32 v[106:107], v[72:73], v[72:73], v[106:107]
	v_pk_fma_f32 v[108:109], v[74:75], v[74:75], v[108:109]
	v_and_b32_e32 v103, 0xffff0000, v77
	v_and_b32_e32 v96, 0xffff0000, v111
	v_and_b32_e32 v102, 0xffff0000, v113
	v_pk_fma_f32 v[106:107], v[86:87], v[86:87], v[106:107]
	v_pk_fma_f32 v[108:109], v[90:91], v[90:91], v[108:109]
	v_and_b32_e32 v89, 0xffff0000, v104
	v_and_b32_e32 v88, 0xffff0000, v114
	v_pk_fma_f32 v[106:107], v[96:97], v[96:97], v[106:107]
	v_pk_fma_f32 v[108:109], v[102:103], v[102:103], v[108:109]
	v_lshlrev_b32_e32 v77, 16, v104
	v_lshlrev_b32_e32 v76, 16, v114
	v_pk_add_f32 v[106:107], v[106:107], v[108:109]
	v_pk_mul_f32 v[108:109], v[88:89], v[88:89]
	v_lshlrev_b32_e32 v93, 16, v105
	v_lshlrev_b32_e32 v92, 16, v115
	v_pk_fma_f32 v[108:109], v[76:77], v[76:77], v[108:109]
	v_and_b32_e32 v105, 0xffff0000, v105
	v_and_b32_e32 v104, 0xffff0000, v115
	v_pk_fma_f32 v[108:109], v[92:93], v[92:93], v[108:109]
	v_and_b32_e32 v117, 0xffff0000, v120
	v_and_b32_e32 v116, 0xffff0000, v122
	v_pk_fma_f32 v[108:109], v[104:105], v[104:105], v[108:109]
	v_lshlrev_b32_e32 v79, 16, v46
	v_lshlrev_b32_e32 v95, 16, v47
	v_and_b32_e32 v99, 0xffff0000, v47
	v_pk_mul_f32 v[46:47], v[82:83], v[82:83]
	v_lshlrev_b32_e32 v114, 16, v122
	v_lshlrev_b32_e32 v115, 16, v120
	v_pk_add_f32 v[106:107], v[106:107], v[108:109]
	v_pk_mul_f32 v[108:109], v[116:117], v[116:117]
	v_pk_fma_f32 v[46:47], v[78:79], v[78:79], v[46:47]
	v_lshlrev_b32_e32 v118, 16, v123
	v_lshlrev_b32_e32 v119, 16, v121
	v_pk_fma_f32 v[108:109], v[114:115], v[114:115], v[108:109]
	v_pk_fma_f32 v[46:47], v[94:95], v[94:95], v[46:47]
	v_and_b32_e32 v121, 0xffff0000, v121
	v_and_b32_e32 v120, 0xffff0000, v123
	v_pk_fma_f32 v[108:109], v[118:119], v[118:119], v[108:109]
	v_pk_fma_f32 v[46:47], v[98:99], v[98:99], v[46:47]
	v_pk_fma_f32 v[108:109], v[120:121], v[120:121], v[108:109]
	v_lshlrev_b32_e32 v110, 16, v131
	v_pk_add_f32 v[106:107], v[106:107], v[108:109]
	v_mov_b32_e32 v108, v136
	v_mov_b32_e32 v109, v46
	v_pk_add_f32 v[122:123], v[106:107], v[108:109]
	v_and_b32_e32 v109, 0xffff0000, v132
	v_and_b32_e32 v108, 0xffff0000, v130
	v_lshlrev_b32_e32 v107, 16, v132
	v_lshlrev_b32_e32 v106, 16, v130
	v_and_b32_e32 v112, 0xffff0000, v131
	v_pk_mul_f32 v[130:131], v[108:109], v[108:109]
	v_lshlrev_b32_e32 v111, 16, v133
	v_pk_fma_f32 v[130:131], v[106:107], v[106:107], v[130:131]
	v_and_b32_e32 v113, 0xffff0000, v133
	v_pk_fma_f32 v[130:131], v[110:111], v[110:111], v[130:131]
	v_mov_b32_e32 v46, v137
	v_pk_fma_f32 v[130:131], v[112:113], v[112:113], v[130:131]
	v_pk_add_f32 v[46:47], v[122:123], v[46:47]
	v_mov_b32_e32 v122, v130
	v_mov_b32_e32 v123, v134
	v_pk_add_f32 v[46:47], v[46:47], v[122:123]
	v_mov_b32_e32 v134, v131
	v_pk_add_f32 v[46:47], v[46:47], v[134:135]
	ds_bpermute_b32 v123, v55, v47
	ds_bpermute_b32 v122, v55, v46
	global_load_dwordx4 v[130:133], v[100:101], off offset:3072 nt
	global_load_dwordx4 v[134:137], v[178:179], off nt
	global_load_dwordx4 v[138:141], v[178:179], off offset:1024 nt
	global_load_dwordx4 v[142:145], v[178:179], off offset:2048 nt
	global_load_dwordx4 v[146:149], v[178:179], off offset:3072 nt
	global_load_dwordx4 v[150:153], v[180:181], off nt
	global_load_dwordx4 v[154:157], v[180:181], off offset:1024 nt
	global_load_dwordx4 v[158:161], v[180:181], off offset:2048 nt
	global_load_dwordx4 v[162:165], v[180:181], off offset:3072 nt
	s_waitcnt lgkmcnt(0)
	v_pk_add_f32 v[46:47], v[46:47], v[122:123]
	ds_bpermute_b32 v123, v124, v47
	ds_bpermute_b32 v122, v124, v46
	v_mov_b32_e32 v186, v73
	v_mov_b32_e32 v187, v81
	v_mov_b32_e32 v188, v87
	v_mov_b32_e32 v189, v97
	s_waitcnt lgkmcnt(0)
	v_pk_add_f32 v[46:47], v[46:47], v[122:123]
	ds_bpermute_b32 v123, v125, v47
	ds_bpermute_b32 v122, v125, v46
	v_mov_b32_e32 v73, v80
	v_mov_b32_e32 v87, v96
	s_waitcnt lgkmcnt(0)
	v_pk_add_f32 v[46:47], v[46:47], v[122:123]
	ds_bpermute_b32 v123, v126, v47
	ds_bpermute_b32 v122, v126, v46
	s_waitcnt lgkmcnt(0)
	v_pk_add_f32 v[44:45], v[46:47], v[122:123]
	ds_bpermute_b32 v47, v127, v45
	ds_bpermute_b32 v46, v127, v44
	v_add_co_u32_e32 v122, vcc, s3, v180
	s_waitcnt lgkmcnt(0)
	v_pk_add_f32 v[44:45], v[44:45], v[46:47]
	ds_bpermute_b32 v47, v128, v45
	ds_bpermute_b32 v46, v128, v44
	v_addc_co_u32_e32 v123, vcc, 0, v181, vcc
	s_waitcnt lgkmcnt(0)
	v_pk_add_f32 v[44:45], v[44:45], v[46:47]
	s_nop 0
	v_pk_fma_f32 v[182:183], v[44:45], s[2:3], v[54:55] op_sel_hi:[1,0,0]
	s_nop 0
	v_mul_f32_e32 v44, 0x4b800000, v183
	v_cmp_gt_f32_e32 vcc, s5, v183
	s_nop 1
	v_cndmask_b32_e32 v44, v183, v44, vcc
	v_rsq_f32_e32 v49, v44
	global_load_dwordx4 v[166:169], v[122:123], off nt
	global_load_dwordx4 v[170:173], v[122:123], off offset:1024 nt
	global_load_dwordx4 v[174:177], v[122:123], off offset:2048 nt
	global_load_dwordx4 v[44:47], v[122:123], off offset:3072 nt
	v_mul_f32_e32 v129, 0x45800000, v49
	v_cndmask_b32_e32 v184, v49, v129, vcc
	v_pk_mul_f32 v[186:187], v[186:187], v[184:185] op_sel_hi:[1,0]
	v_pk_mul_f32 v[188:189], v[188:189], v[184:185] op_sel_hi:[1,0]
	v_pk_fma_f32 v[40:41], v[0:1], v[186:187], v[40:41]
	v_pk_fma_f32 v[42:43], v[2:3], v[188:189], v[42:43]
	global_store_dwordx4 v[100:101], v[40:43], off
	v_cmp_gt_f32_e32 vcc, s5, v182
	s_nop 0
	v_mov_b32_e32 v40, v75
	v_mov_b32_e32 v41, v85
	v_mov_b32_e32 v42, v91
	v_mov_b32_e32 v43, v103
	v_pk_mul_f32 v[40:41], v[40:41], v[184:185] op_sel_hi:[1,0]
	v_pk_mul_f32 v[42:43], v[42:43], v[184:185] op_sel_hi:[1,0]
	v_pk_fma_f32 v[36:37], v[4:5], v[40:41], v[36:37]
	v_pk_fma_f32 v[38:39], v[6:7], v[42:43], v[38:39]
	global_store_dwordx4 v[100:101], v[36:39], off offset:1024
	v_mov_b32_e32 v75, v84
	v_mov_b32_e32 v91, v102
	v_mov_b32_e32 v36, v77
	v_mov_b32_e32 v37, v89
	v_mov_b32_e32 v38, v93
	v_mov_b32_e32 v39, v105
	v_pk_mul_f32 v[36:37], v[36:37], v[184:185] op_sel_hi:[1,0]
	v_pk_mul_f32 v[38:39], v[38:39], v[184:185] op_sel_hi:[1,0]
	v_pk_fma_f32 v[32:33], v[8:9], v[36:37], v[32:33]
	v_pk_fma_f32 v[34:35], v[10:11], v[38:39], v[34:35]
	global_store_dwordx4 v[100:101], v[32:35], off offset:2048
	v_mul_f32_e32 v36, 0x4b800000, v182
	v_cndmask_b32_e32 v36, v182, v36, vcc
	v_mov_b32_e32 v32, v115
	v_mov_b32_e32 v33, v117
	v_mov_b32_e32 v34, v119
	v_mov_b32_e32 v35, v121
	v_pk_mul_f32 v[32:33], v[32:33], v[184:185] op_sel_hi:[1,0]
	v_pk_mul_f32 v[34:35], v[34:35], v[184:185] op_sel_hi:[1,0]
	s_waitcnt vmcnt(15)
	v_pk_fma_f32 v[32:33], v[12:13], v[32:33], v[130:131]
	v_pk_fma_f32 v[34:35], v[14:15], v[34:35], v[132:133]
	global_store_dwordx4 v[100:101], v[32:35], off offset:3072
	v_rsq_f32_e32 v36, v36
	v_mov_b32_e32 v77, v88
	v_mov_b32_e32 v32, v78
	v_mov_b32_e32 v33, v82
	v_mov_b32_e32 v34, v94
	v_mov_b32_e32 v35, v98
	v_pk_mul_f32 v[32:33], v[32:33], v[184:185] op_sel_hi:[1,0]
	v_pk_mul_f32 v[34:35], v[34:35], v[184:185] op_sel_hi:[1,0]
	s_waitcnt vmcnt(15)
	v_pk_fma_f32 v[32:33], v[16:17], v[32:33], v[134:135]
	v_pk_fma_f32 v[34:35], v[18:19], v[34:35], v[136:137]
	v_mov_b32_e32 v82, v79
	v_mov_b32_e32 v98, v95
	global_store_dwordx4 v[178:179], v[32:35], off
	v_mov_b32_e32 v93, v104
	v_mov_b32_e32 v115, v116
	v_pk_mul_f32 v[32:33], v[82:83], v[184:185] op_sel_hi:[1,0]
	v_pk_mul_f32 v[34:35], v[98:99], v[184:185] op_sel_hi:[1,0]
	s_waitcnt vmcnt(15)
	v_pk_fma_f32 v[32:33], v[20:21], v[32:33], v[138:139]
	v_pk_fma_f32 v[34:35], v[22:23], v[34:35], v[140:141]
	global_store_dwordx4 v[178:179], v[32:35], off offset:1024
	v_mov_b32_e32 v119, v120
	s_nop 0
	v_mov_b32_e32 v32, v64
	v_mov_b32_e32 v33, v66
	v_mov_b32_e32 v34, v68
	v_mov_b32_e32 v35, v70
	v_pk_mul_f32 v[32:33], v[32:33], v[184:185] op_sel_hi:[1,0]
	v_pk_mul_f32 v[34:35], v[34:35], v[184:185] op_sel_hi:[1,0]
	s_waitcnt vmcnt(15)
	v_pk_fma_f32 v[32:33], v[24:25], v[32:33], v[142:143]
	v_pk_fma_f32 v[34:35], v[26:27], v[34:35], v[144:145]
	v_mov_b32_e32 v66, v65
	v_mov_b32_e32 v70, v69
	global_store_dwordx4 v[178:179], v[32:35], off offset:2048
	s_nop 1
	v_pk_mul_f32 v[32:33], v[66:67], v[184:185] op_sel_hi:[1,0]
	v_pk_mul_f32 v[34:35], v[70:71], v[184:185] op_sel_hi:[1,0]
	s_waitcnt vmcnt(15)
	v_pk_fma_f32 v[32:33], v[28:29], v[32:33], v[146:147]
	v_pk_fma_f32 v[34:35], v[30:31], v[34:35], v[148:149]
	global_store_dwordx4 v[178:179], v[32:35], off offset:3072
	s_nop 1
	v_mul_f32_e32 v32, 0x45800000, v36
	v_cndmask_b32_e32 v36, v36, v32, vcc
	v_pk_mul_f32 v[32:33], v[72:73], v[36:37] op_sel_hi:[1,0]
	v_pk_mul_f32 v[34:35], v[86:87], v[36:37] op_sel_hi:[1,0]
	s_waitcnt vmcnt(15)
	v_pk_fma_f32 v[32:33], v[0:1], v[32:33], v[150:151]
	v_pk_fma_f32 v[34:35], v[2:3], v[34:35], v[152:153]
	global_store_dwordx4 v[180:181], v[32:35], off
	v_cmp_lt_i32_e32 vcc, s6, v48
	s_or_b64 s[0:1], vcc, s[0:1]
	v_pk_mul_f32 v[32:33], v[74:75], v[36:37] op_sel_hi:[1,0]
	v_pk_mul_f32 v[34:35], v[90:91], v[36:37] op_sel_hi:[1,0]
	s_waitcnt vmcnt(15)
	v_pk_fma_f32 v[32:33], v[4:5], v[32:33], v[154:155]
	v_pk_fma_f32 v[34:35], v[6:7], v[34:35], v[156:157]
	global_store_dwordx4 v[180:181], v[32:35], off offset:1024
	s_nop 1
	v_pk_mul_f32 v[32:33], v[76:77], v[36:37] op_sel_hi:[1,0]
	v_pk_mul_f32 v[34:35], v[92:93], v[36:37] op_sel_hi:[1,0]
	s_waitcnt vmcnt(15)
	v_pk_fma_f32 v[32:33], v[8:9], v[32:33], v[158:159]
	v_pk_fma_f32 v[34:35], v[10:11], v[34:35], v[160:161]
	global_store_dwordx4 v[180:181], v[32:35], off offset:2048
	s_nop 1
	v_pk_mul_f32 v[32:33], v[114:115], v[36:37] op_sel_hi:[1,0]
	v_pk_mul_f32 v[34:35], v[118:119], v[36:37] op_sel_hi:[1,0]
	s_waitcnt vmcnt(15)
	v_pk_fma_f32 v[32:33], v[12:13], v[32:33], v[162:163]
	v_pk_fma_f32 v[34:35], v[14:15], v[34:35], v[164:165]
	global_store_dwordx4 v[180:181], v[32:35], off offset:3072
	s_nop 1
	v_mov_b32_e32 v32, v58
	v_mov_b32_e32 v33, v56
	v_mov_b32_e32 v34, v62
	v_mov_b32_e32 v35, v60
	v_pk_mul_f32 v[32:33], v[32:33], v[36:37] op_sel_hi:[1,0]
	v_pk_mul_f32 v[34:35], v[34:35], v[36:37] op_sel_hi:[1,0]
	s_waitcnt vmcnt(15)
	v_pk_fma_f32 v[32:33], v[16:17], v[32:33], v[166:167]
	v_pk_fma_f32 v[34:35], v[18:19], v[34:35], v[168:169]
	v_mov_b32_e32 v56, v59
	v_mov_b32_e32 v60, v63
	global_store_dwordx4 v[122:123], v[32:35], off
	s_nop 1
	v_pk_mul_f32 v[32:33], v[56:57], v[36:37] op_sel_hi:[1,0]
	v_pk_mul_f32 v[34:35], v[60:61], v[36:37] op_sel_hi:[1,0]
	s_waitcnt vmcnt(15)
	v_pk_fma_f32 v[32:33], v[20:21], v[32:33], v[170:171]
	v_pk_fma_f32 v[34:35], v[22:23], v[34:35], v[172:173]
	global_store_dwordx4 v[122:123], v[32:35], off offset:1024
	s_nop 1
	v_mov_b32_e32 v32, v106
	v_mov_b32_e32 v33, v108
	v_mov_b32_e32 v34, v110
	v_mov_b32_e32 v35, v112
	v_pk_mul_f32 v[32:33], v[32:33], v[36:37] op_sel_hi:[1,0]
	v_pk_mul_f32 v[34:35], v[34:35], v[36:37] op_sel_hi:[1,0]
	s_waitcnt vmcnt(15)
	v_pk_fma_f32 v[32:33], v[24:25], v[32:33], v[174:175]
	v_pk_fma_f32 v[34:35], v[26:27], v[34:35], v[176:177]
	v_mov_b32_e32 v108, v107
	v_mov_b32_e32 v112, v111
	global_store_dwordx4 v[122:123], v[32:35], off offset:2048
	s_nop 1
	v_pk_mul_f32 v[32:33], v[108:109], v[36:37] op_sel_hi:[1,0]
	v_pk_mul_f32 v[34:35], v[112:113], v[36:37] op_sel_hi:[1,0]
	s_waitcnt vmcnt(15)
	v_pk_fma_f32 v[32:33], v[28:29], v[32:33], v[44:45]
	v_pk_fma_f32 v[34:35], v[30:31], v[34:35], v[46:47]
	global_store_dwordx4 v[122:123], v[32:35], off offset:3072
	s_andn2_b64 exec, exec, s[0:1]
	s_cbranch_execnz .LBB0_1491
